# w_in and FFN-up tail weight copies split over all 256 workgroups (unit owners join after their unit)
# baseline (speedup 1.0000x reference)
.LBB0_258:
	s_abs_i32 s76, s42
	v_cvt_f32_u32_e32 v2, s76
	s_sub_i32 s6, 0, s76
	v_rcp_iflag_f32_e32 v2, v2
	s_nop 0
	v_mul_f32_e32 v2, 0x4f7ffffe, v2
	v_cvt_u32_f32_e32 v2, v2
	s_nop 0
	v_readfirstlane_b32 s77, v2
	s_mul_i32 s6, s6, s77
	s_mul_hi_u32 s6, s77, s6
	s_add_i32 s77, s77, s6
	s_mul_hi_u32 s6, s77, 0xd70
	s_mul_i32 s6, s6, s76
	s_sub_i32 s6, 0xd70, s6
	s_sub_i32 s7, s6, s76
	s_cmp_ge_u32 s6, s76
	s_cselect_b32 s6, s7, s6
	s_sub_i32 s7, s6, s76
	s_cmp_ge_u32 s6, s76
	s_cselect_b32 s17, s7, s6
	s_sub_i32 s16, s42, s17
	s_cmp_lt_i32 s2, s17
	s_cselect_b64 s[6:7], -1, 0
	s_and_b64 s[14:15], s[6:7], exec
	s_cselect_b32 s16, 0, s16
	s_cmp_eq_u32 s17, 0
	s_cselect_b64 s[14:15], -1, 0
	s_and_b64 s[18:19], s[14:15], exec
	s_cselect_b32 s16, s42, s16
	s_cmpk_lg_i32 s42, 0x100
	s_cbranch_scc1 .Lup_generic
	s_movk_i32 s16, 0x100
	s_mov_b32 s6, s2
	s_branch .Lup_go
.Lup_generic:
	s_cmp_lg_u32 s16, 0
	s_cbranch_scc0 .LBB0_270
	s_sub_i32 s17, s2, s17
	s_and_b64 s[6:7], s[6:7], exec
	s_cselect_b32 s17, 0, s17
	s_and_b64 s[6:7], s[14:15], exec
	s_cselect_b32 s6, s2, s17
.Lup_go:
	s_lshl_b32 s7, s6, 3
	s_add_i32 s34, s7, s3
	s_cmpk_gt_i32 s34, 0x1fff
	s_cbranch_scc1 .LBB0_270
	v_lshlrev_b32_e32 v3, 4, v218
	v_lshlrev_b32_e32 v4, 1, v218
	v_and_b32_e32 v2, 28, v200
	v_and_b32_e32 v3, 0x80, v3
	v_and_b32_e32 v4, 0x60, v4
	s_lshl_b32 s6, s6, 6
	s_lshl_b32 s7, s3, 3
	s_lshl_b32 s35, s16, 3
	v_or3_b32 v24, v3, v4, v2
	s_add_i32 s47, s6, s7
	s_lshl_b32 s50, s16, 6
	s_mov_b32 s7, 0
	v_mov_b32_e32 v3, 0
	s_mov_b64 s[14:15], 0x2000
	s_mov_b64 s[16:17], 0x4000
	s_mov_b64 s[18:19], 0x6000
	s_mov_b64 s[20:21], 0x8000
	s_mov_b64 s[22:23], 0xa000
	s_mov_b64 s[24:25], 0xc000
	s_mov_b64 s[26:27], 0xe000
	s_movk_i32 s51, 0x1800
	s_movk_i32 s60, 0xc00
	s_mov_b64 s[28:29], 0x12000
	s_mov_b64 s[30:31], 0x18000
	s_mov_b64 s[36:37], 0x1e000
	s_mov_b64 s[38:39], 0x24000
	s_mov_b64 s[44:45], 0x2a000
	s_movk_i32 s61, 0x7fff
	s_mov_b32 s62, 0xffff0000
	s_movk_i32 s63, 0x2000
	s_branch .LBB0_262

.LBB0_671:
	s_mul_hi_u32 s6, s77, 0x780
	s_mul_i32 s6, s6, s76
	s_sub_i32 s6, 0x780, s6
	s_sub_i32 s7, s6, s76
	s_cmp_ge_u32 s6, s76
	s_cselect_b32 s6, s7, s6
	s_sub_i32 s7, s6, s76
	s_cmp_ge_u32 s6, s76
	s_cselect_b32 s10, s7, s6
	s_sub_i32 s11, s42, s10
	s_cmp_lt_i32 s2, s10
	s_cselect_b64 s[6:7], -1, 0
	s_and_b64 s[8:9], s[6:7], exec
	s_cselect_b32 s11, 0, s11
	s_cmp_eq_u32 s10, 0
	s_cselect_b64 s[8:9], -1, 0
	s_waitcnt lgkmcnt(0)
	s_and_b64 s[18:19], s[8:9], exec
	s_cselect_b32 s18, s42, s11
	s_cmpk_lg_i32 s42, 0x100
	s_cbranch_scc1 .Lwin_generic
	s_movk_i32 s18, 0x100
	s_mov_b32 s6, s2
	s_branch .Lwin_go
.Lwin_generic:
	s_cmp_eq_u32 s18, 0
	s_cbranch_scc1 .LBB0_687
	s_sub_i32 s10, s2, s10
	s_and_b64 s[6:7], s[6:7], exec
	s_cselect_b32 s10, 0, s10
	s_and_b64 s[6:7], s[8:9], exec
	s_cselect_b32 s6, s2, s10
